# P10: the per-round s_barrier moved to the start of the sweeps (after the token prologues)
# baseline (speedup 1.0000x reference)
; __device__ __forceinline__ void phase10(const Args& a, LAS unsigned char* lds, int tid, int wave, int lane, int vcu, int G, int emask, bool probe) {
;     ...
;         u32x4 hqh[GTK][2];
; #pragma unroll
;         for (int tk = 0; tk < GTK; ++tk)
; #pragma unroll
;             for (int h = 0; h < 2; ++h)
; #pragma unroll
;                 for (int e = 0; e < 4; ++e) hqh[tk][h][e] = (unsigned)__shfl((int)hq[tk][e], 32 * h + lq);
.LBB0_1697:
	s_barrier
	v_add_u32_e32 v150, v67, v75
	ds_read_u16 v0, v150
	ds_read_u16 v2, v150 offset:4
	s_waitcnt lgkmcnt(13)
	ds_read_u16 v4, v150 offset:8
	s_waitcnt lgkmcnt(13)
	ds_read_u16 v5, v150 offset:12
	s_waitcnt lgkmcnt(5)
	ds_read_u16 v6, v150 offset:256
	s_waitcnt lgkmcnt(5)
	ds_read_u16 v7, v150 offset:260
	ds_read_u16 v8, v150 offset:264
	ds_read_u16 v9, v150 offset:268
	s_waitcnt lgkmcnt(7)
	v_and_b32_e32 v0, 0x3fff, v0
	v_lshlrev_b32_sdwa v68, v231, v0 dst_sel:DWORD dst_unused:UNUSED_PAD src0_sel:DWORD src1_sel:WORD_0
	s_waitcnt lgkmcnt(6)
	v_and_b32_e32 v2, 0x3fff, v2
	v_lshl_add_u64 v[0:1], v[76:77], 0, v[68:69]
	v_lshlrev_b32_sdwa v68, v231, v2 dst_sel:DWORD dst_unused:UNUSED_PAD src0_sel:DWORD src1_sel:WORD_0
	v_lshl_add_u64 v[2:3], v[76:77], 0, v[68:69]
	global_load_dwordx4 v[44:47], v[0:1], off
	global_load_dwordx4 v[36:39], v[2:3], off
	s_waitcnt lgkmcnt(5)
	v_and_b32_e32 v0, 0x3fff, v4
	v_lshlrev_b32_sdwa v68, v231, v0 dst_sel:DWORD dst_unused:UNUSED_PAD src0_sel:DWORD src1_sel:WORD_0
	s_waitcnt lgkmcnt(4)
	v_and_b32_e32 v2, 0x3fff, v5
	v_lshl_add_u64 v[0:1], v[76:77], 0, v[68:69]
	v_lshlrev_b32_sdwa v68, v231, v2 dst_sel:DWORD dst_unused:UNUSED_PAD src0_sel:DWORD src1_sel:WORD_0
	v_lshl_add_u64 v[2:3], v[76:77], 0, v[68:69]
	global_load_dwordx4 v[40:43], v[0:1], off
	global_load_dwordx4 v[32:35], v[2:3], off
	s_waitcnt lgkmcnt(3)
	v_and_b32_e32 v0, 0x3fff, v6
	v_lshlrev_b32_sdwa v68, v231, v0 dst_sel:DWORD dst_unused:UNUSED_PAD src0_sel:DWORD src1_sel:WORD_0
	s_waitcnt lgkmcnt(2)
	v_and_b32_e32 v2, 0x3fff, v7
	v_lshl_add_u64 v[0:1], v[76:77], 0, v[68:69]
	v_lshlrev_b32_sdwa v68, v231, v2 dst_sel:DWORD dst_unused:UNUSED_PAD src0_sel:DWORD src1_sel:WORD_0
	v_lshl_add_u64 v[2:3], v[76:77], 0, v[68:69]
	global_load_dwordx4 v[28:31], v[0:1], off
	global_load_dwordx4 v[16:19], v[2:3], off
	s_waitcnt lgkmcnt(1)
	v_and_b32_e32 v0, 0x3fff, v8
	v_lshlrev_b32_sdwa v68, v231, v0 dst_sel:DWORD dst_unused:UNUSED_PAD src0_sel:DWORD src1_sel:WORD_0
	s_waitcnt lgkmcnt(0)
	v_and_b32_e32 v2, 0x3fff, v9
	ds_read_u16 v4, v150 offset:512
	v_lshl_add_u64 v[0:1], v[76:77], 0, v[68:69]
	v_lshlrev_b32_sdwa v68, v231, v2 dst_sel:DWORD dst_unused:UNUSED_PAD src0_sel:DWORD src1_sel:WORD_0
	v_lshl_add_u64 v[2:3], v[76:77], 0, v[68:69]
	global_load_dwordx4 v[24:27], v[0:1], off
	global_load_dwordx4 v[12:15], v[2:3], off
	ds_read_u16 v2, v150 offset:516
	ds_read_u16 v8, v150 offset:520
	ds_read_u16 v9, v150 offset:524
	s_waitcnt lgkmcnt(3)
	v_and_b32_e32 v0, 0x3fff, v4
	v_lshlrev_b32_sdwa v68, v231, v0 dst_sel:DWORD dst_unused:UNUSED_PAD src0_sel:DWORD src1_sel:WORD_0
	s_waitcnt lgkmcnt(2)
	v_and_b32_e32 v2, 0x3fff, v2
	v_lshl_add_u64 v[0:1], v[76:77], 0, v[68:69]
	v_lshlrev_b32_sdwa v68, v231, v2 dst_sel:DWORD dst_unused:UNUSED_PAD src0_sel:DWORD src1_sel:WORD_0
	v_lshl_add_u64 v[2:3], v[76:77], 0, v[68:69]
	global_load_dwordx4 v[20:23], v[0:1], off
	global_load_dwordx4 v[4:7], v[2:3], off
	s_waitcnt lgkmcnt(1)
	v_and_b32_e32 v0, 0x3fff, v8
	v_lshlrev_b32_sdwa v68, v231, v0 dst_sel:DWORD dst_unused:UNUSED_PAD src0_sel:DWORD src1_sel:WORD_0
	s_waitcnt lgkmcnt(0)
	v_and_b32_e32 v2, 0x3fff, v9
	v_lshl_add_u64 v[0:1], v[76:77], 0, v[68:69]
	v_lshlrev_b32_sdwa v68, v231, v2 dst_sel:DWORD dst_unused:UNUSED_PAD src0_sel:DWORD src1_sel:WORD_0
	v_lshl_add_u64 v[2:3], v[76:77], 0, v[68:69]
	global_load_dwordx4 v[8:11], v[0:1], off
	s_nop 0
	global_load_dwordx4 v[0:3], v[2:3], off
	ds_bpermute_b32 v109, v221, v50
	ds_bpermute_b32 v108, v221, v48
	ds_bpermute_b32 v107, v221, v51
	ds_bpermute_b32 v106, v221, v49
	ds_bpermute_b32 v62, v222, v50
	ds_bpermute_b32 v61, v222, v51
	ds_bpermute_b32 v105, v221, v57
	ds_bpermute_b32 v104, v221, v52
	ds_bpermute_b32 v103, v221, v58
	ds_bpermute_b32 v102, v221, v53
	ds_bpermute_b32 v60, v222, v57
	ds_bpermute_b32 v59, v222, v58
	ds_bpermute_b32 v101, v221, v94
	ds_bpermute_b32 v100, v221, v63
	ds_bpermute_b32 v51, v221, v95
	ds_bpermute_b32 v50, v221, v99
	ds_bpermute_b32 v58, v222, v94
	ds_bpermute_b32 v57, v222, v95
	s_mov_b32 s34, -8
	v_mov_b32_e32 v94, v223
	v_mov_b32_e32 v95, v71
	s_branch .LBB0_1699
